# stack of small changes: batched prep staging loads, no invalidate at same-XCD group barriers, kernarg spill lanes written once
# speedup vs baseline: 1.0075x; 1.0075x over previous
.LBB0_285:
	s_and_b32 s10, s7, 0xfc0
	s_sub_i32 s17, 15, s10
	s_add_i32 s11, s7, -16
	s_waitcnt vmcnt(0)
	s_barrier
	v_mov_b32_e32 v108, 0
	v_mov_b32_e32 v109, 0
	v_mov_b32_e32 v110, 0
	v_mov_b32_e32 v111, 0
	v_cmp_lt_i32_e32 vcc, s17, v47
	s_and_saveexec_b64 s[2:3], vcc
	s_cbranch_execz .Lpp_0
	v_add_u32_e32 v148, s11, v47
	v_mad_i64_i32 v[108:109], s[42:43], v148, s22, v[32:33]
	global_load_dwordx4 v[108:111], v[108:109], off
.Lpp_0:
	s_or_b64 exec, exec, s[2:3]
	v_mov_b32_e32 v112, 0
	v_mov_b32_e32 v113, 0
	v_mov_b32_e32 v114, 0
	v_mov_b32_e32 v115, 0
	v_cmp_lt_i32_e32 vcc, s17, v48
	s_and_saveexec_b64 s[2:3], vcc
	s_cbranch_execz .Lpp_1
	v_add_u32_e32 v148, s11, v48
	v_mad_i64_i32 v[112:113], s[42:43], v148, s22, v[32:33]
	global_load_dwordx4 v[112:115], v[112:113], off
.Lpp_1:
	s_or_b64 exec, exec, s[2:3]
	v_mov_b32_e32 v116, 0
	v_mov_b32_e32 v117, 0
	v_mov_b32_e32 v118, 0
	v_mov_b32_e32 v119, 0
	v_cmp_lt_i32_e32 vcc, s17, v49
	s_and_saveexec_b64 s[2:3], vcc
	s_cbranch_execz .Lpp_2
	v_add_u32_e32 v148, s11, v49
	v_mad_i64_i32 v[116:117], s[42:43], v148, s22, v[32:33]
	global_load_dwordx4 v[116:119], v[116:117], off
.Lpp_2:
	s_or_b64 exec, exec, s[2:3]
	v_mov_b32_e32 v120, 0
	v_mov_b32_e32 v121, 0
	v_mov_b32_e32 v122, 0
	v_mov_b32_e32 v123, 0
	v_cmp_lt_i32_e32 vcc, s17, v50
	s_and_saveexec_b64 s[2:3], vcc
	s_cbranch_execz .Lpp_3
	v_add_u32_e32 v148, s11, v50
	v_mad_i64_i32 v[120:121], s[42:43], v148, s22, v[32:33]
	global_load_dwordx4 v[120:123], v[120:121], off
.Lpp_3:
	s_or_b64 exec, exec, s[2:3]
	v_mov_b32_e32 v124, 0
	v_mov_b32_e32 v125, 0
	v_mov_b32_e32 v126, 0
	v_mov_b32_e32 v127, 0
	v_cmp_lt_i32_e32 vcc, s17, v51
	s_and_saveexec_b64 s[2:3], vcc
	s_cbranch_execz .Lpp_4
	v_add_u32_e32 v148, s11, v51
	v_mad_i64_i32 v[124:125], s[42:43], v148, s22, v[32:33]
	global_load_dwordx4 v[124:127], v[124:125], off
.Lpp_4:
	s_or_b64 exec, exec, s[2:3]
	v_mov_b32_e32 v128, 0
	v_mov_b32_e32 v129, 0
	v_mov_b32_e32 v130, 0
	v_mov_b32_e32 v131, 0
	v_cmp_lt_i32_e32 vcc, s17, v52
	s_and_saveexec_b64 s[2:3], vcc
	s_cbranch_execz .Lpp_5
	v_add_u32_e32 v148, s11, v52
	v_mad_i64_i32 v[128:129], s[42:43], v148, s22, v[32:33]
	global_load_dwordx4 v[128:131], v[128:129], off
.Lpp_5:
	s_or_b64 exec, exec, s[2:3]
	v_mov_b32_e32 v132, 0
	v_mov_b32_e32 v133, 0
	v_mov_b32_e32 v134, 0
	v_mov_b32_e32 v135, 0
	v_cmp_lt_i32_e32 vcc, s17, v53
	s_and_saveexec_b64 s[2:3], vcc
	s_cbranch_execz .Lpp_6
	v_add_u32_e32 v148, s11, v53
	v_mad_i64_i32 v[132:133], s[42:43], v148, s22, v[32:33]
	global_load_dwordx4 v[132:135], v[132:133], off
.Lpp_6:
	s_or_b64 exec, exec, s[2:3]
	v_mov_b32_e32 v136, 0
	v_mov_b32_e32 v137, 0
	v_mov_b32_e32 v138, 0
	v_mov_b32_e32 v139, 0
	v_cmp_lt_i32_e32 vcc, s17, v54
	s_and_saveexec_b64 s[2:3], vcc
	s_cbranch_execz .Lpp_7
	v_add_u32_e32 v148, s11, v54
	v_mad_i64_i32 v[136:137], s[42:43], v148, s22, v[32:33]
	global_load_dwordx4 v[136:139], v[136:137], off
.Lpp_7:
	s_or_b64 exec, exec, s[2:3]
	v_mov_b32_e32 v140, 0
	v_mov_b32_e32 v141, 0
	v_mov_b32_e32 v142, 0
	v_mov_b32_e32 v143, 0
	v_cmp_lt_i32_e32 vcc, s17, v55
	s_and_saveexec_b64 s[2:3], vcc
	s_cbranch_execz .Lpp_8
	v_add_u32_e32 v148, s11, v55
	v_mad_i64_i32 v[140:141], s[42:43], v148, s22, v[32:33]
	global_load_dwordx4 v[140:143], v[140:141], off
.Lpp_8:
	s_or_b64 exec, exec, s[2:3]
	v_mov_b32_e32 v144, 0
	v_mov_b32_e32 v145, 0
	v_mov_b32_e32 v146, 0
	v_mov_b32_e32 v147, 0
	v_cmp_lt_i32_e32 vcc, s17, v56
	s_and_saveexec_b64 s[2:3], vcc
	s_cbranch_execz .Lpp_9
	v_add_u32_e32 v148, s11, v56
	v_mad_i64_i32 v[144:145], s[42:43], v148, s22, v[32:33]
	global_load_dwordx4 v[144:147], v[144:145], off
.Lpp_9:
	s_or_b64 exec, exec, s[2:3]
	v_add_u32_e32 v38, s7, v40
	v_mov_b64_e32 v[0:1], s[0:1]
	v_mad_i64_i32 v[24:25], s[2:3], v38, s22, v[0:1]
	v_lshl_add_u64 v[4:5], v[24:25], 0, v[64:65]
	global_load_dwordx4 v[26:29], v[4:5], off offset:1024
	global_load_dwordx4 v[86:89], v[4:5], off offset:1152
	global_load_dwordx4 v[90:93], v[4:5], off offset:1280
	global_load_dwordx4 v[16:19], v[4:5], off offset:1408
	global_load_dwordx4 v[8:11], v[4:5], off offset:1536
	global_load_dwordx4 v[0:3], v[4:5], off offset:1664
	global_load_dwordx4 v[94:97], v[4:5], off offset:1792
	global_load_dwordx4 v[20:23], v[4:5], off offset:1920
	global_load_dwordx4 v[12:15], v[4:5], off offset:2048
	s_nop 0
	global_load_dwordx4 v[4:7], v[4:5], off offset:2176
	v_ashrrev_i32_e32 v39, 31, v38
	s_waitcnt vmcnt(10)
	ds_write_b128 v58, v[108:111]
	ds_write_b128 v59, v[112:115]
	ds_write_b128 v60, v[116:119]
	ds_write_b128 v61, v[120:123]
	ds_write_b128 v62, v[124:127]
	ds_write_b128 v63, v[128:131]
	ds_write_b128 v66, v[132:135]
	ds_write_b128 v67, v[136:139]
	ds_write_b128 v68, v[140:143]
	ds_write_b128 v69, v[144:147]
	s_waitcnt vmcnt(9)
	v_lshlrev_b32_e32 v31, 16, v27
	v_lshlrev_b32_e32 v30, 16, v26
	v_and_b32_e32 v27, 0xffff0000, v27
	v_and_b32_e32 v26, 0xffff0000, v26
	v_pk_mul_f32 v[26:27], v[26:27], v[26:27]
	s_waitcnt vmcnt(7)
	v_lshlrev_b32_e32 v99, 16, v91
	v_pk_fma_f32 v[26:27], v[30:31], v[30:31], v[26:27]
	v_lshlrev_b32_e32 v31, 16, v29
	v_lshlrev_b32_e32 v30, 16, v28
	v_and_b32_e32 v29, 0xffff0000, v29
	v_and_b32_e32 v28, 0xffff0000, v28
	v_pk_mul_f32 v[28:29], v[28:29], v[28:29]
	v_add_f32_e32 v26, v26, v27
	v_pk_fma_f32 v[28:29], v[30:31], v[30:31], v[28:29]
	v_lshlrev_b32_e32 v31, 16, v87
	v_lshlrev_b32_e32 v30, 16, v86
	v_and_b32_e32 v87, 0xffff0000, v87
	v_and_b32_e32 v86, 0xffff0000, v86
	v_pk_mul_f32 v[86:87], v[86:87], v[86:87]
	v_add_f32_e32 v26, v28, v26
	v_pk_fma_f32 v[30:31], v[30:31], v[30:31], v[86:87]
	v_lshlrev_b32_e32 v87, 16, v89
	v_lshlrev_b32_e32 v86, 16, v88
	v_and_b32_e32 v89, 0xffff0000, v89
	v_and_b32_e32 v88, 0xffff0000, v88
	v_add_f32_e32 v26, v29, v26
	v_pk_mul_f32 v[88:89], v[88:89], v[88:89]
	v_add_f32_e32 v26, v30, v26
	v_pk_fma_f32 v[86:87], v[86:87], v[86:87], v[88:89]
	v_add_f32_e32 v26, v31, v26
	v_add_f32_e32 v26, v86, v26
	v_pk_add_f32 v[28:29], v[86:87], v[26:27] op_sel_hi:[1,0]
	v_lshlrev_b32_e32 v26, 16, v90
	v_and_b32_e32 v27, 0xffff0000, v90
	v_mul_f32_e32 v28, v26, v26
	v_pk_fma_f32 v[30:31], v[26:27], v[26:27], v[28:29] op_sel_hi:[1,1,0]
	v_and_b32_e32 v91, 0xffff0000, v91
	s_waitcnt vmcnt(3)
	v_and_b32_e32 v90, 0xffff0000, v94
	v_lshlrev_b32_e32 v26, 16, v95
	v_and_b32_e32 v28, 0xffff0000, v95
	v_and_b32_e32 v89, 0xffff0000, v92
	v_lshlrev_b32_e32 v98, 16, v94
	v_mul_f32_e32 v30, v26, v26
	v_mul_f32_e32 v28, v28, v28
	v_and_b32_e32 v88, 0xffff0000, v96
	v_pk_mul_f32 v[90:91], v[90:91], v[90:91]
	v_lshlrev_b32_e32 v87, 16, v92
	v_lshlrev_b32_e32 v86, 16, v96
	v_pk_fma_f32 v[90:91], v[98:99], v[98:99], v[90:91]
	v_pk_add_f32 v[28:29], v[30:31], v[28:29]
	v_pk_mul_f32 v[30:31], v[88:89], v[88:89]
	v_pk_add_f32 v[28:29], v[90:91], v[28:29]
	v_pk_fma_f32 v[30:31], v[86:87], v[86:87], v[30:31]
	v_and_b32_e32 v87, 0xffff0000, v93
	v_and_b32_e32 v86, 0xffff0000, v97
	v_pk_add_f32 v[28:29], v[30:31], v[28:29]
	v_lshlrev_b32_e32 v31, 16, v93
	v_lshlrev_b32_e32 v30, 16, v97
	v_pk_mul_f32 v[86:87], v[86:87], v[86:87]
	s_waitcnt vmcnt(0)
	v_lshlrev_b32_e32 v26, 16, v5
	v_pk_fma_f32 v[30:31], v[30:31], v[30:31], v[86:87]
	v_and_b32_e32 v87, 0xffff0000, v16
	v_and_b32_e32 v86, 0xffff0000, v20
	v_pk_add_f32 v[28:29], v[30:31], v[28:29]
	v_lshlrev_b32_e32 v31, 16, v16
	v_lshlrev_b32_e32 v30, 16, v20
	v_pk_mul_f32 v[86:87], v[86:87], v[86:87]
	v_and_b32_e32 v16, 0xffff0000, v21
	v_pk_fma_f32 v[30:31], v[30:31], v[30:31], v[86:87]
	v_lshlrev_b32_e32 v20, 16, v22
	v_pk_add_f32 v[28:29], v[30:31], v[28:29]
	v_lshlrev_b32_e32 v31, 16, v17
	v_and_b32_e32 v17, 0xffff0000, v17
	v_lshlrev_b32_e32 v30, 16, v21
	v_pk_mul_f32 v[16:17], v[16:17], v[16:17]
	v_lshlrev_b32_e32 v21, 16, v18
	v_pk_fma_f32 v[16:17], v[30:31], v[30:31], v[16:17]
	v_lshlrev_b32_e32 v27, 16, v1
	v_pk_add_f32 v[16:17], v[16:17], v[28:29]
	v_and_b32_e32 v29, 0xffff0000, v18
	v_and_b32_e32 v28, 0xffff0000, v22
	v_pk_mul_f32 v[28:29], v[28:29], v[28:29]
	v_and_b32_e32 v18, 0xffff0000, v23
	v_pk_fma_f32 v[20:21], v[20:21], v[20:21], v[28:29]
	v_and_b32_e32 v1, 0xffff0000, v1
	v_pk_add_f32 v[16:17], v[20:21], v[16:17]
	v_lshlrev_b32_e32 v21, 16, v19
	v_and_b32_e32 v19, 0xffff0000, v19
	v_lshlrev_b32_e32 v20, 16, v23
	v_pk_mul_f32 v[18:19], v[18:19], v[18:19]
	s_nop 0
	v_pk_fma_f32 v[18:19], v[20:21], v[20:21], v[18:19]
	v_and_b32_e32 v21, 0xffff0000, v8
	v_and_b32_e32 v20, 0xffff0000, v12
	v_pk_add_f32 v[16:17], v[18:19], v[16:17]
	v_lshlrev_b32_e32 v19, 16, v8
	v_lshlrev_b32_e32 v18, 16, v12
	v_pk_mul_f32 v[20:21], v[20:21], v[20:21]
	v_and_b32_e32 v8, 0xffff0000, v13
	v_pk_fma_f32 v[18:19], v[18:19], v[18:19], v[20:21]
	v_lshlrev_b32_e32 v12, 16, v14
	v_pk_add_f32 v[16:17], v[18:19], v[16:17]
	v_lshlrev_b32_e32 v19, 16, v9
	v_and_b32_e32 v9, 0xffff0000, v9
	v_lshlrev_b32_e32 v18, 16, v13
	v_pk_mul_f32 v[8:9], v[8:9], v[8:9]
	v_lshlrev_b32_e32 v13, 16, v10
	v_pk_fma_f32 v[8:9], v[18:19], v[18:19], v[8:9]
	v_and_b32_e32 v19, 0xffff0000, v0
	v_pk_add_f32 v[8:9], v[8:9], v[16:17]
	v_and_b32_e32 v17, 0xffff0000, v10
	v_and_b32_e32 v16, 0xffff0000, v14
	v_pk_mul_f32 v[16:17], v[16:17], v[16:17]
	v_and_b32_e32 v10, 0xffff0000, v15
	v_pk_fma_f32 v[12:13], v[12:13], v[12:13], v[16:17]
	v_lshlrev_b32_e32 v17, 16, v11
	v_and_b32_e32 v11, 0xffff0000, v11
	v_lshlrev_b32_e32 v16, 16, v15
	v_pk_mul_f32 v[10:11], v[10:11], v[10:11]
	v_lshlrev_b32_e32 v15, 16, v0
	v_lshlrev_b32_e32 v14, 16, v4
	v_and_b32_e32 v18, 0xffff0000, v4
	v_and_b32_e32 v0, 0xffff0000, v5
	v_pk_add_f32 v[4:5], v[12:13], v[8:9]
	v_pk_fma_f32 v[8:9], v[16:17], v[16:17], v[10:11]
	v_and_b32_e32 v13, 0xffff0000, v2
	v_pk_add_f32 v[4:5], v[8:9], v[4:5]
	v_pk_mul_f32 v[8:9], v[18:19], v[18:19]
	v_and_b32_e32 v12, 0xffff0000, v6
	v_pk_fma_f32 v[8:9], v[14:15], v[14:15], v[8:9]
	v_pk_mul_f32 v[0:1], v[0:1], v[0:1]
	v_lshlrev_b32_e32 v11, 16, v2
	v_lshlrev_b32_e32 v10, 16, v6
	v_pk_mul_f32 v[12:13], v[12:13], v[12:13]
	v_pk_fma_f32 v[0:1], v[26:27], v[26:27], v[0:1]
	v_pk_fma_f32 v[10:11], v[10:11], v[10:11], v[12:13]
	v_lshlrev_b32_e32 v13, 16, v3
	v_and_b32_e32 v3, 0xffff0000, v3
	v_and_b32_e32 v2, 0xffff0000, v7
	v_pk_add_f32 v[4:5], v[8:9], v[4:5]
	v_lshlrev_b32_e32 v12, 16, v7
	v_pk_mul_f32 v[2:3], v[2:3], v[2:3]
	v_pk_add_f32 v[0:1], v[0:1], v[4:5]
	v_pk_fma_f32 v[2:3], v[12:13], v[12:13], v[2:3]
	v_pk_add_f32 v[0:1], v[10:11], v[0:1]
	s_nop 0
	v_pk_add_f32 v[0:1], v[2:3], v[0:1]
	ds_bpermute_b32 v3, v41, v1
	ds_bpermute_b32 v2, v41, v0
	s_waitcnt lgkmcnt(0)
	v_pk_add_f32 v[0:1], v[0:1], v[2:3]
	ds_bpermute_b32 v3, v42, v1
	ds_bpermute_b32 v2, v42, v0
	s_waitcnt lgkmcnt(0)
	v_pk_add_f32 v[0:1], v[0:1], v[2:3]
	ds_bpermute_b32 v3, v43, v1
	ds_bpermute_b32 v2, v43, v0
	s_and_saveexec_b64 s[2:3], s[40:41]
	s_cbranch_execz .LBB0_307
	s_mov_b32 s42, 0x3b800000
	s_waitcnt lgkmcnt(0)
	v_pk_add_f32 v[0:1], v[0:1], v[2:3]
	s_mov_b32 s43, 0x3b2aaaab
	v_pk_fma_f32 v[0:1], v[0:1], s[42:43], v[188:189] op_sel_hi:[1,1,0]
	v_lshlrev_b64 v[4:5], 2, v[38:39]
	v_mul_f32_e32 v2, 0x4b800000, v1
	v_cmp_gt_f32_e32 vcc, s73, v1
	v_cmp_gt_f32_e64 s[42:43], s73, v0
	v_lshl_add_u64 v[6:7], s[56:57], 0, v[4:5]
	v_cndmask_b32_e32 v1, v1, v2, vcc
	v_rsq_f32_e32 v1, v1
	v_mul_f32_e32 v2, 0x4b800000, v0
	v_cndmask_b32_e64 v0, v0, v2, s[42:43]
	v_rsq_f32_e32 v0, v0
	v_mul_f32_e32 v2, 0x45800000, v1
	v_cndmask_b32_e32 v1, v1, v2, vcc
	global_store_dword v[6:7], v1, off sc1
	v_mul_f32_e32 v1, 0x45800000, v0
	v_cndmask_b32_e64 v2, v0, v1, s[42:43]
	v_lshl_add_u64 v[0:1], s[76:77], 0, v[4:5]
	global_store_dword v[0:1], v2, off sc1
